# grid barriers 2..16 hand-written: completing workgroup releases every XCD flag directly (no top-level relay hop), static generation numbers
# speedup vs baseline: 1.0111x; 1.0012x over previous
.LBB0_141:
	s_waitcnt vmcnt(0)
	v_mov_b32_e32 v0, v205
	s_barrier
	s_nop 0
	v_cmp_eq_u32_e32 vcc, 0, v0
	s_and_saveexec_b64 s[0:1], vcc
	s_cbranch_execz .LBB0_193
	v_mov_b32_e32 v0, 0x12000
	ds_read_b64 v[2:3], v0
	s_getreg_b32 s98, hwreg(HW_REG_XCC_ID, 0, 4)
	s_and_b32 s98, s98, 15
	s_lshl_b32 s98, s98, 8
	v_mov_b32_e32 v1, 1
	s_add_u32 s100, s98, 0x1dc01400
	s_add_u32 s101, s98, 0x1dc02400
	v_mov_b32_e32 v4, s100
	s_waitcnt vmcnt(0) expcnt(0) lgkmcnt(0)
	global_atomic_add v5, v4, v1, s[26:27] sc0
	v_mul_lo_u32 v6, v2, 2
	s_waitcnt vmcnt(0)
	v_add_u32_e32 v5, 1, v5
	v_cmp_eq_u32_e32 vcc, v5, v6
	s_cbranch_vccz .Lxb1_spin
	buffer_wbl2 sc1
	s_waitcnt vmcnt(0)
	v_mov_b32_e32 v4, 0x1dc03400
	global_atomic_add v5, v4, v1, s[26:27] sc0
	v_mul_lo_u32 v6, v3, 2
	s_waitcnt vmcnt(0)
	v_add_u32_e32 v5, 1, v5
	v_cmp_eq_u32_e32 vcc, v5, v6
	s_cbranch_vccz .Lxb1_spin
	v_mov_b32_e32 v4, 0x1dc02400
	global_atomic_add v4, v1, s[26:27]
	global_atomic_add v4, v1, s[26:27] offset:256
	global_atomic_add v4, v1, s[26:27] offset:512
	global_atomic_add v4, v1, s[26:27] offset:768
	global_atomic_add v4, v1, s[26:27] offset:1024
	global_atomic_add v4, v1, s[26:27] offset:1280
	global_atomic_add v4, v1, s[26:27] offset:1536
	global_atomic_add v4, v1, s[26:27] offset:1792
	global_atomic_add v4, v1, s[26:27] offset:2048
	global_atomic_add v4, v1, s[26:27] offset:2304
	global_atomic_add v4, v1, s[26:27] offset:2560
	global_atomic_add v4, v1, s[26:27] offset:2816
	global_atomic_add v4, v1, s[26:27] offset:3072
	global_atomic_add v4, v1, s[26:27] offset:3328
	global_atomic_add v4, v1, s[26:27] offset:3584
	global_atomic_add v4, v1, s[26:27] offset:3840
	s_waitcnt vmcnt(0)
	s_branch .Lxb1_done
.Lxb1_spin:
	v_mov_b32_e32 v4, s101
	s_mov_b32 s99, 0
.Lxb1_loop:
	global_load_dword v5, v4, s[26:27] sc1
	s_waitcnt vmcnt(0)
	v_cmp_ne_u32_e32 vcc, 1, v5
	s_cbranch_vccnz .Lxb1_done
	s_sleep 1
	s_add_u32 s99, s99, 1
	s_cmp_lt_u32 s99, 0x8000
	s_cbranch_scc1 .Lxb1_loop
.Lxb1_done:
	buffer_inv sc1
	s_waitcnt vmcnt(0)

.LBB0_200:
	s_waitcnt vmcnt(0)
	v_mov_b32_e32 v0, v205
	s_barrier
	s_nop 0
	v_cmp_eq_u32_e32 vcc, 0, v0
	s_and_saveexec_b64 s[0:1], vcc
	s_cbranch_execz .LBB0_252
	v_mov_b32_e32 v0, 0x12000
	ds_read_b64 v[2:3], v0
	s_getreg_b32 s98, hwreg(HW_REG_XCC_ID, 0, 4)
	s_and_b32 s98, s98, 15
	s_lshl_b32 s98, s98, 8
	v_mov_b32_e32 v1, 1
	s_add_u32 s100, s98, 0x1dc01400
	s_add_u32 s101, s98, 0x1dc02400
	v_mov_b32_e32 v4, s100
	s_waitcnt vmcnt(0) expcnt(0) lgkmcnt(0)
	global_atomic_add v5, v4, v1, s[26:27] sc0
	v_mul_lo_u32 v6, v2, 3
	s_waitcnt vmcnt(0)
	v_add_u32_e32 v5, 1, v5
	v_cmp_eq_u32_e32 vcc, v5, v6
	s_cbranch_vccz .Lxb2_spin
	buffer_wbl2 sc1
	s_waitcnt vmcnt(0)
	v_mov_b32_e32 v4, 0x1dc03400
	global_atomic_add v5, v4, v1, s[26:27] sc0
	v_mul_lo_u32 v6, v3, 3
	s_waitcnt vmcnt(0)
	v_add_u32_e32 v5, 1, v5
	v_cmp_eq_u32_e32 vcc, v5, v6
	s_cbranch_vccz .Lxb2_spin
	v_mov_b32_e32 v4, 0x1dc02400
	global_atomic_add v4, v1, s[26:27]
	global_atomic_add v4, v1, s[26:27] offset:256
	global_atomic_add v4, v1, s[26:27] offset:512
	global_atomic_add v4, v1, s[26:27] offset:768
	global_atomic_add v4, v1, s[26:27] offset:1024
	global_atomic_add v4, v1, s[26:27] offset:1280
	global_atomic_add v4, v1, s[26:27] offset:1536
	global_atomic_add v4, v1, s[26:27] offset:1792
	global_atomic_add v4, v1, s[26:27] offset:2048
	global_atomic_add v4, v1, s[26:27] offset:2304
	global_atomic_add v4, v1, s[26:27] offset:2560
	global_atomic_add v4, v1, s[26:27] offset:2816
	global_atomic_add v4, v1, s[26:27] offset:3072
	global_atomic_add v4, v1, s[26:27] offset:3328
	global_atomic_add v4, v1, s[26:27] offset:3584
	global_atomic_add v4, v1, s[26:27] offset:3840
	s_waitcnt vmcnt(0)
	s_branch .Lxb2_done

.Lxb2_loop:
	global_load_dword v5, v4, s[26:27] sc1
	s_waitcnt vmcnt(0)
	v_cmp_ne_u32_e32 vcc, 2, v5
	s_cbranch_vccnz .Lxb2_done
	s_sleep 1
	s_add_u32 s99, s99, 1
	s_cmp_lt_u32 s99, 0x8000
	s_cbranch_scc1 .Lxb2_loop

.LBB0_257:
	s_or_b64 exec, exec, s[10:11]
	s_waitcnt vmcnt(0)
	v_mov_b32_e32 v0, v205
	s_barrier
	s_nop 0
	v_cmp_eq_u32_e32 vcc, 0, v0
	s_and_saveexec_b64 s[0:1], vcc
	s_cbranch_execz .LBB0_309
	v_mov_b32_e32 v0, 0x12000
	ds_read_b64 v[2:3], v0
	s_getreg_b32 s98, hwreg(HW_REG_XCC_ID, 0, 4)
	s_and_b32 s98, s98, 15
	s_lshl_b32 s98, s98, 8
	v_mov_b32_e32 v1, 1
	s_add_u32 s100, s98, 0x1dc01400
	s_add_u32 s101, s98, 0x1dc02400
	v_mov_b32_e32 v4, s100
	s_waitcnt vmcnt(0) expcnt(0) lgkmcnt(0)
	global_atomic_add v5, v4, v1, s[26:27] sc0
	v_mul_lo_u32 v6, v2, 4
	s_waitcnt vmcnt(0)
	v_add_u32_e32 v5, 1, v5
	v_cmp_eq_u32_e32 vcc, v5, v6
	s_cbranch_vccz .Lxb3_spin
	buffer_wbl2 sc1
	s_waitcnt vmcnt(0)
	v_mov_b32_e32 v4, 0x1dc03400
	global_atomic_add v5, v4, v1, s[26:27] sc0
	v_mul_lo_u32 v6, v3, 4
	s_waitcnt vmcnt(0)
	v_add_u32_e32 v5, 1, v5
	v_cmp_eq_u32_e32 vcc, v5, v6
	s_cbranch_vccz .Lxb3_spin
	v_mov_b32_e32 v4, 0x1dc02400
	global_atomic_add v4, v1, s[26:27]
	global_atomic_add v4, v1, s[26:27] offset:256
	global_atomic_add v4, v1, s[26:27] offset:512
	global_atomic_add v4, v1, s[26:27] offset:768
	global_atomic_add v4, v1, s[26:27] offset:1024
	global_atomic_add v4, v1, s[26:27] offset:1280
	global_atomic_add v4, v1, s[26:27] offset:1536
	global_atomic_add v4, v1, s[26:27] offset:1792
	global_atomic_add v4, v1, s[26:27] offset:2048
	global_atomic_add v4, v1, s[26:27] offset:2304
	global_atomic_add v4, v1, s[26:27] offset:2560
	global_atomic_add v4, v1, s[26:27] offset:2816
	global_atomic_add v4, v1, s[26:27] offset:3072
	global_atomic_add v4, v1, s[26:27] offset:3328
	global_atomic_add v4, v1, s[26:27] offset:3584
	global_atomic_add v4, v1, s[26:27] offset:3840
	s_waitcnt vmcnt(0)
	s_branch .Lxb3_done

.Lxb3_loop:
	global_load_dword v5, v4, s[26:27] sc1
	s_waitcnt vmcnt(0)
	v_cmp_ne_u32_e32 vcc, 3, v5
	s_cbranch_vccnz .Lxb3_done
	s_sleep 1
	s_add_u32 s99, s99, 1
	s_cmp_lt_u32 s99, 0x8000
	s_cbranch_scc1 .Lxb3_loop

.LBB0_314:
	s_waitcnt vmcnt(0)
	v_mov_b32_e32 v0, v205
	s_barrier
	s_nop 0
	v_cmp_eq_u32_e32 vcc, 0, v0
	s_and_saveexec_b64 s[0:1], vcc
	s_cbranch_execz .LBB0_366
	v_mov_b32_e32 v0, 0x12000
	ds_read_b64 v[2:3], v0
	s_getreg_b32 s98, hwreg(HW_REG_XCC_ID, 0, 4)
	s_and_b32 s98, s98, 15
	s_lshl_b32 s98, s98, 8
	v_mov_b32_e32 v1, 1
	s_add_u32 s100, s98, 0x1dc01400
	s_add_u32 s101, s98, 0x1dc02400
	v_mov_b32_e32 v4, s100
	s_waitcnt vmcnt(0) expcnt(0) lgkmcnt(0)
	global_atomic_add v5, v4, v1, s[26:27] sc0
	v_mul_lo_u32 v6, v2, 5
	s_waitcnt vmcnt(0)
	v_add_u32_e32 v5, 1, v5
	v_cmp_eq_u32_e32 vcc, v5, v6
	s_cbranch_vccz .Lxb4_spin
	buffer_wbl2 sc1
	s_waitcnt vmcnt(0)
	v_mov_b32_e32 v4, 0x1dc03400
	global_atomic_add v5, v4, v1, s[26:27] sc0
	v_mul_lo_u32 v6, v3, 5
	s_waitcnt vmcnt(0)
	v_add_u32_e32 v5, 1, v5
	v_cmp_eq_u32_e32 vcc, v5, v6
	s_cbranch_vccz .Lxb4_spin
	v_mov_b32_e32 v4, 0x1dc02400
	global_atomic_add v4, v1, s[26:27]
	global_atomic_add v4, v1, s[26:27] offset:256
	global_atomic_add v4, v1, s[26:27] offset:512
	global_atomic_add v4, v1, s[26:27] offset:768
	global_atomic_add v4, v1, s[26:27] offset:1024
	global_atomic_add v4, v1, s[26:27] offset:1280
	global_atomic_add v4, v1, s[26:27] offset:1536
	global_atomic_add v4, v1, s[26:27] offset:1792
	global_atomic_add v4, v1, s[26:27] offset:2048
	global_atomic_add v4, v1, s[26:27] offset:2304
	global_atomic_add v4, v1, s[26:27] offset:2560
	global_atomic_add v4, v1, s[26:27] offset:2816
	global_atomic_add v4, v1, s[26:27] offset:3072
	global_atomic_add v4, v1, s[26:27] offset:3328
	global_atomic_add v4, v1, s[26:27] offset:3584
	global_atomic_add v4, v1, s[26:27] offset:3840
	s_waitcnt vmcnt(0)
	s_branch .Lxb4_done

.Lxb4_loop:
	global_load_dword v5, v4, s[26:27] sc1
	s_waitcnt vmcnt(0)
	v_cmp_ne_u32_e32 vcc, 4, v5
	s_cbranch_vccnz .Lxb4_done
	s_sleep 1
	s_add_u32 s99, s99, 1
	s_cmp_lt_u32 s99, 0x8000
	s_cbranch_scc1 .Lxb4_loop

.LBB0_381:
	s_waitcnt vmcnt(0)
	v_mov_b32_e32 v0, v205
	s_barrier
	s_nop 0
	v_cmp_eq_u32_e32 vcc, 0, v0
	s_and_saveexec_b64 s[4:5], vcc
	s_cbranch_execz .LBB0_433
	v_mov_b32_e32 v0, 0x12000
	ds_read_b64 v[2:3], v0
	s_getreg_b32 s98, hwreg(HW_REG_XCC_ID, 0, 4)
	s_and_b32 s98, s98, 15
	s_lshl_b32 s98, s98, 8
	v_mov_b32_e32 v1, 1
	s_add_u32 s100, s98, 0x1dc01400
	s_add_u32 s101, s98, 0x1dc02400
	v_mov_b32_e32 v4, s100
	s_waitcnt vmcnt(0) expcnt(0) lgkmcnt(0)
	global_atomic_add v5, v4, v1, s[26:27] sc0
	v_mul_lo_u32 v6, v2, 6
	s_waitcnt vmcnt(0)
	v_add_u32_e32 v5, 1, v5
	v_cmp_eq_u32_e32 vcc, v5, v6
	s_cbranch_vccz .Lxb5_spin
	buffer_wbl2 sc1
	s_waitcnt vmcnt(0)
	v_mov_b32_e32 v4, 0x1dc03400
	global_atomic_add v5, v4, v1, s[26:27] sc0
	v_mul_lo_u32 v6, v3, 6
	s_waitcnt vmcnt(0)
	v_add_u32_e32 v5, 1, v5
	v_cmp_eq_u32_e32 vcc, v5, v6
	s_cbranch_vccz .Lxb5_spin
	v_mov_b32_e32 v4, 0x1dc02400
	global_atomic_add v4, v1, s[26:27]
	global_atomic_add v4, v1, s[26:27] offset:256
	global_atomic_add v4, v1, s[26:27] offset:512
	global_atomic_add v4, v1, s[26:27] offset:768
	global_atomic_add v4, v1, s[26:27] offset:1024
	global_atomic_add v4, v1, s[26:27] offset:1280
	global_atomic_add v4, v1, s[26:27] offset:1536
	global_atomic_add v4, v1, s[26:27] offset:1792
	global_atomic_add v4, v1, s[26:27] offset:2048
	global_atomic_add v4, v1, s[26:27] offset:2304
	global_atomic_add v4, v1, s[26:27] offset:2560
	global_atomic_add v4, v1, s[26:27] offset:2816
	global_atomic_add v4, v1, s[26:27] offset:3072
	global_atomic_add v4, v1, s[26:27] offset:3328
	global_atomic_add v4, v1, s[26:27] offset:3584
	global_atomic_add v4, v1, s[26:27] offset:3840
	s_waitcnt vmcnt(0)
	s_branch .Lxb5_done

.Lxb5_loop:
	global_load_dword v5, v4, s[26:27] sc1
	s_waitcnt vmcnt(0)
	v_cmp_ne_u32_e32 vcc, 5, v5
	s_cbranch_vccnz .Lxb5_done
	s_sleep 1
	s_add_u32 s99, s99, 1
	s_cmp_lt_u32 s99, 0x8000
	s_cbranch_scc1 .Lxb5_loop

.LBB0_436:
	s_or_b64 exec, exec, s[6:7]
	s_waitcnt vmcnt(0)
	v_mov_b32_e32 v0, v205
	s_barrier
	s_nop 0
	v_cmp_eq_u32_e32 vcc, 0, v0
	s_and_saveexec_b64 s[4:5], vcc
	s_cbranch_execz .LBB0_488
	v_mov_b32_e32 v0, 0x12000
	ds_read_b64 v[2:3], v0
	s_getreg_b32 s98, hwreg(HW_REG_XCC_ID, 0, 4)
	s_and_b32 s98, s98, 15
	s_lshl_b32 s98, s98, 8
	v_mov_b32_e32 v1, 1
	s_add_u32 s100, s98, 0x1dc01400
	s_add_u32 s101, s98, 0x1dc02400
	v_mov_b32_e32 v4, s100
	s_waitcnt vmcnt(0) expcnt(0) lgkmcnt(0)
	global_atomic_add v5, v4, v1, s[26:27] sc0
	v_mul_lo_u32 v6, v2, 7
	s_waitcnt vmcnt(0)
	v_add_u32_e32 v5, 1, v5
	v_cmp_eq_u32_e32 vcc, v5, v6
	s_cbranch_vccz .Lxb6_spin
	buffer_wbl2 sc1
	s_waitcnt vmcnt(0)
	v_mov_b32_e32 v4, 0x1dc03400
	global_atomic_add v5, v4, v1, s[26:27] sc0
	v_mul_lo_u32 v6, v3, 7
	s_waitcnt vmcnt(0)
	v_add_u32_e32 v5, 1, v5
	v_cmp_eq_u32_e32 vcc, v5, v6
	s_cbranch_vccz .Lxb6_spin
	v_mov_b32_e32 v4, 0x1dc02400
	global_atomic_add v4, v1, s[26:27]
	global_atomic_add v4, v1, s[26:27] offset:256
	global_atomic_add v4, v1, s[26:27] offset:512
	global_atomic_add v4, v1, s[26:27] offset:768
	global_atomic_add v4, v1, s[26:27] offset:1024
	global_atomic_add v4, v1, s[26:27] offset:1280
	global_atomic_add v4, v1, s[26:27] offset:1536
	global_atomic_add v4, v1, s[26:27] offset:1792
	global_atomic_add v4, v1, s[26:27] offset:2048
	global_atomic_add v4, v1, s[26:27] offset:2304
	global_atomic_add v4, v1, s[26:27] offset:2560
	global_atomic_add v4, v1, s[26:27] offset:2816
	global_atomic_add v4, v1, s[26:27] offset:3072
	global_atomic_add v4, v1, s[26:27] offset:3328
	global_atomic_add v4, v1, s[26:27] offset:3584
	global_atomic_add v4, v1, s[26:27] offset:3840
	s_waitcnt vmcnt(0)
	s_branch .Lxb6_done

.Lxb6_loop:
	global_load_dword v5, v4, s[26:27] sc1
	s_waitcnt vmcnt(0)
	v_cmp_ne_u32_e32 vcc, 6, v5
	s_cbranch_vccnz .Lxb6_done
	s_sleep 1
	s_add_u32 s99, s99, 1
	s_cmp_lt_u32 s99, 0x8000
	s_cbranch_scc1 .Lxb6_loop

.LBB0_503:
	s_waitcnt vmcnt(0)
	v_mov_b32_e32 v0, v205
	s_barrier
	s_nop 0
	v_cmp_eq_u32_e32 vcc, 0, v0
	s_and_saveexec_b64 s[4:5], vcc
	s_cbranch_execz .LBB0_555
	v_mov_b32_e32 v0, 0x12000
	ds_read_b64 v[2:3], v0
	s_getreg_b32 s98, hwreg(HW_REG_XCC_ID, 0, 4)
	s_and_b32 s98, s98, 15
	s_lshl_b32 s98, s98, 8
	v_mov_b32_e32 v1, 1
	s_add_u32 s100, s98, 0x1dc01400
	s_add_u32 s101, s98, 0x1dc02400
	v_mov_b32_e32 v4, s100
	s_waitcnt vmcnt(0) expcnt(0) lgkmcnt(0)
	global_atomic_add v5, v4, v1, s[26:27] sc0
	v_mul_lo_u32 v6, v2, 8
	s_waitcnt vmcnt(0)
	v_add_u32_e32 v5, 1, v5
	v_cmp_eq_u32_e32 vcc, v5, v6
	s_cbranch_vccz .Lxb7_spin
	buffer_wbl2 sc1
	s_waitcnt vmcnt(0)
	v_mov_b32_e32 v4, 0x1dc03400
	global_atomic_add v5, v4, v1, s[26:27] sc0
	v_mul_lo_u32 v6, v3, 8
	s_waitcnt vmcnt(0)
	v_add_u32_e32 v5, 1, v5
	v_cmp_eq_u32_e32 vcc, v5, v6
	s_cbranch_vccz .Lxb7_spin
	v_mov_b32_e32 v4, 0x1dc02400
	global_atomic_add v4, v1, s[26:27]
	global_atomic_add v4, v1, s[26:27] offset:256
	global_atomic_add v4, v1, s[26:27] offset:512
	global_atomic_add v4, v1, s[26:27] offset:768
	global_atomic_add v4, v1, s[26:27] offset:1024
	global_atomic_add v4, v1, s[26:27] offset:1280
	global_atomic_add v4, v1, s[26:27] offset:1536
	global_atomic_add v4, v1, s[26:27] offset:1792
	global_atomic_add v4, v1, s[26:27] offset:2048
	global_atomic_add v4, v1, s[26:27] offset:2304
	global_atomic_add v4, v1, s[26:27] offset:2560
	global_atomic_add v4, v1, s[26:27] offset:2816
	global_atomic_add v4, v1, s[26:27] offset:3072
	global_atomic_add v4, v1, s[26:27] offset:3328
	global_atomic_add v4, v1, s[26:27] offset:3584
	global_atomic_add v4, v1, s[26:27] offset:3840
	s_waitcnt vmcnt(0)
	s_branch .Lxb7_done

.Lxb7_loop:
	global_load_dword v5, v4, s[26:27] sc1
	s_waitcnt vmcnt(0)
	v_cmp_ne_u32_e32 vcc, 7, v5
	s_cbranch_vccnz .Lxb7_done
	s_sleep 1
	s_add_u32 s99, s99, 1
	s_cmp_lt_u32 s99, 0x8000
	s_cbranch_scc1 .Lxb7_loop

.LBB0_578:
	s_or_b64 exec, exec, s[6:7]
	s_waitcnt vmcnt(0)
	v_mov_b32_e32 v0, v205
	s_barrier
	s_nop 0
	v_cmp_eq_u32_e32 vcc, 0, v0
	s_and_saveexec_b64 s[4:5], vcc
	s_cbranch_execz .LBB0_630
	v_mov_b32_e32 v0, 0x12000
	ds_read_b64 v[2:3], v0
	s_getreg_b32 s98, hwreg(HW_REG_XCC_ID, 0, 4)
	s_and_b32 s98, s98, 15
	s_lshl_b32 s98, s98, 8
	v_mov_b32_e32 v1, 1
	s_add_u32 s100, s98, 0x1dc01400
	s_add_u32 s101, s98, 0x1dc02400
	v_mov_b32_e32 v4, s100
	s_waitcnt vmcnt(0) expcnt(0) lgkmcnt(0)
	global_atomic_add v5, v4, v1, s[26:27] sc0
	v_mul_lo_u32 v6, v2, 9
	s_waitcnt vmcnt(0)
	v_add_u32_e32 v5, 1, v5
	v_cmp_eq_u32_e32 vcc, v5, v6
	s_cbranch_vccz .Lxb8_spin
	buffer_wbl2 sc1
	s_waitcnt vmcnt(0)
	v_mov_b32_e32 v4, 0x1dc03400
	global_atomic_add v5, v4, v1, s[26:27] sc0
	v_mul_lo_u32 v6, v3, 9
	s_waitcnt vmcnt(0)
	v_add_u32_e32 v5, 1, v5
	v_cmp_eq_u32_e32 vcc, v5, v6
	s_cbranch_vccz .Lxb8_spin
	v_mov_b32_e32 v4, 0x1dc02400
	global_atomic_add v4, v1, s[26:27]
	global_atomic_add v4, v1, s[26:27] offset:256
	global_atomic_add v4, v1, s[26:27] offset:512
	global_atomic_add v4, v1, s[26:27] offset:768
	global_atomic_add v4, v1, s[26:27] offset:1024
	global_atomic_add v4, v1, s[26:27] offset:1280
	global_atomic_add v4, v1, s[26:27] offset:1536
	global_atomic_add v4, v1, s[26:27] offset:1792
	global_atomic_add v4, v1, s[26:27] offset:2048
	global_atomic_add v4, v1, s[26:27] offset:2304
	global_atomic_add v4, v1, s[26:27] offset:2560
	global_atomic_add v4, v1, s[26:27] offset:2816
	global_atomic_add v4, v1, s[26:27] offset:3072
	global_atomic_add v4, v1, s[26:27] offset:3328
	global_atomic_add v4, v1, s[26:27] offset:3584
	global_atomic_add v4, v1, s[26:27] offset:3840
	s_waitcnt vmcnt(0)
	s_branch .Lxb8_done

.Lxb8_loop:
	global_load_dword v5, v4, s[26:27] sc1
	s_waitcnt vmcnt(0)
	v_cmp_ne_u32_e32 vcc, 8, v5
	s_cbranch_vccnz .Lxb8_done
	s_sleep 1
	s_add_u32 s99, s99, 1
	s_cmp_lt_u32 s99, 0x8000
	s_cbranch_scc1 .Lxb8_loop

.LBB0_637:
	s_or_b64 exec, exec, s[6:7]
	s_waitcnt vmcnt(0)
	v_mov_b32_e32 v0, v205
	s_barrier
	s_nop 0
	v_cmp_eq_u32_e32 vcc, 0, v0
	s_and_saveexec_b64 s[4:5], vcc
	s_cbranch_execz .LBB0_689
	v_mov_b32_e32 v0, 0x12000
	ds_read_b64 v[2:3], v0
	s_getreg_b32 s98, hwreg(HW_REG_XCC_ID, 0, 4)
	s_and_b32 s98, s98, 15
	s_lshl_b32 s98, s98, 8
	v_mov_b32_e32 v1, 1
	s_add_u32 s100, s98, 0x1dc01400
	s_add_u32 s101, s98, 0x1dc02400
	v_mov_b32_e32 v4, s100
	s_waitcnt vmcnt(0) expcnt(0) lgkmcnt(0)
	global_atomic_add v5, v4, v1, s[26:27] sc0
	v_mul_lo_u32 v6, v2, 10
	s_waitcnt vmcnt(0)
	v_add_u32_e32 v5, 1, v5
	v_cmp_eq_u32_e32 vcc, v5, v6
	s_cbranch_vccz .Lxb9_spin
	buffer_wbl2 sc1
	s_waitcnt vmcnt(0)
	v_mov_b32_e32 v4, 0x1dc03400
	global_atomic_add v5, v4, v1, s[26:27] sc0
	v_mul_lo_u32 v6, v3, 10
	s_waitcnt vmcnt(0)
	v_add_u32_e32 v5, 1, v5
	v_cmp_eq_u32_e32 vcc, v5, v6
	s_cbranch_vccz .Lxb9_spin
	v_mov_b32_e32 v4, 0x1dc02400
	global_atomic_add v4, v1, s[26:27]
	global_atomic_add v4, v1, s[26:27] offset:256
	global_atomic_add v4, v1, s[26:27] offset:512
	global_atomic_add v4, v1, s[26:27] offset:768
	global_atomic_add v4, v1, s[26:27] offset:1024
	global_atomic_add v4, v1, s[26:27] offset:1280
	global_atomic_add v4, v1, s[26:27] offset:1536
	global_atomic_add v4, v1, s[26:27] offset:1792
	global_atomic_add v4, v1, s[26:27] offset:2048
	global_atomic_add v4, v1, s[26:27] offset:2304
	global_atomic_add v4, v1, s[26:27] offset:2560
	global_atomic_add v4, v1, s[26:27] offset:2816
	global_atomic_add v4, v1, s[26:27] offset:3072
	global_atomic_add v4, v1, s[26:27] offset:3328
	global_atomic_add v4, v1, s[26:27] offset:3584
	global_atomic_add v4, v1, s[26:27] offset:3840
	s_waitcnt vmcnt(0)
	s_branch .Lxb9_done

.Lxb9_loop:
	global_load_dword v5, v4, s[26:27] sc1
	s_waitcnt vmcnt(0)
	v_cmp_ne_u32_e32 vcc, 9, v5
	s_cbranch_vccnz .Lxb9_done
	s_sleep 1
	s_add_u32 s99, s99, 1
	s_cmp_lt_u32 s99, 0x8000
	s_cbranch_scc1 .Lxb9_loop

.LBB0_710:
	s_waitcnt vmcnt(0)
	v_mov_b32_e32 v0, v205
	s_barrier
	s_nop 0
	v_cmp_eq_u32_e32 vcc, 0, v0
	s_and_saveexec_b64 s[4:5], vcc
	s_cbranch_execz .LBB0_762
	v_mov_b32_e32 v0, 0x12000
	ds_read_b64 v[2:3], v0
	s_getreg_b32 s98, hwreg(HW_REG_XCC_ID, 0, 4)
	s_and_b32 s98, s98, 15
	s_lshl_b32 s98, s98, 8
	v_mov_b32_e32 v1, 1
	s_add_u32 s100, s98, 0x1dc01400
	s_add_u32 s101, s98, 0x1dc02400
	v_mov_b32_e32 v4, s100
	s_waitcnt vmcnt(0) expcnt(0) lgkmcnt(0)
	global_atomic_add v5, v4, v1, s[26:27] sc0
	v_mul_lo_u32 v6, v2, 11
	s_waitcnt vmcnt(0)
	v_add_u32_e32 v5, 1, v5
	v_cmp_eq_u32_e32 vcc, v5, v6
	s_cbranch_vccz .Lxb10_spin
	buffer_wbl2 sc1
	s_waitcnt vmcnt(0)
	v_mov_b32_e32 v4, 0x1dc03400
	global_atomic_add v5, v4, v1, s[26:27] sc0
	v_mul_lo_u32 v6, v3, 11
	s_waitcnt vmcnt(0)
	v_add_u32_e32 v5, 1, v5
	v_cmp_eq_u32_e32 vcc, v5, v6
	s_cbranch_vccz .Lxb10_spin
	v_mov_b32_e32 v4, 0x1dc02400
	global_atomic_add v4, v1, s[26:27]
	global_atomic_add v4, v1, s[26:27] offset:256
	global_atomic_add v4, v1, s[26:27] offset:512
	global_atomic_add v4, v1, s[26:27] offset:768
	global_atomic_add v4, v1, s[26:27] offset:1024
	global_atomic_add v4, v1, s[26:27] offset:1280
	global_atomic_add v4, v1, s[26:27] offset:1536
	global_atomic_add v4, v1, s[26:27] offset:1792
	global_atomic_add v4, v1, s[26:27] offset:2048
	global_atomic_add v4, v1, s[26:27] offset:2304
	global_atomic_add v4, v1, s[26:27] offset:2560
	global_atomic_add v4, v1, s[26:27] offset:2816
	global_atomic_add v4, v1, s[26:27] offset:3072
	global_atomic_add v4, v1, s[26:27] offset:3328
	global_atomic_add v4, v1, s[26:27] offset:3584
	global_atomic_add v4, v1, s[26:27] offset:3840
	s_waitcnt vmcnt(0)
	s_branch .Lxb10_done

.Lxb10_loop:
	global_load_dword v5, v4, s[26:27] sc1
	s_waitcnt vmcnt(0)
	v_cmp_ne_u32_e32 vcc, 10, v5
	s_cbranch_vccnz .Lxb10_done
	s_sleep 1
	s_add_u32 s99, s99, 1
	s_cmp_lt_u32 s99, 0x8000
	s_cbranch_scc1 .Lxb10_loop

.LBB0_781:
	s_waitcnt vmcnt(0)
	v_mov_b32_e32 v0, v205
	s_barrier
	s_nop 0
	v_cmp_eq_u32_e32 vcc, 0, v0
	s_and_saveexec_b64 s[4:5], vcc
	s_cbranch_execz .LBB0_833
	v_mov_b32_e32 v0, 0x12000
	ds_read_b64 v[2:3], v0
	s_getreg_b32 s98, hwreg(HW_REG_XCC_ID, 0, 4)
	s_and_b32 s98, s98, 15
	s_lshl_b32 s98, s98, 8
	v_mov_b32_e32 v1, 1
	s_add_u32 s100, s98, 0x1dc01400
	s_add_u32 s101, s98, 0x1dc02400
	v_mov_b32_e32 v4, s100
	s_waitcnt vmcnt(0) expcnt(0) lgkmcnt(0)
	global_atomic_add v5, v4, v1, s[26:27] sc0
	v_mul_lo_u32 v6, v2, 12
	s_waitcnt vmcnt(0)
	v_add_u32_e32 v5, 1, v5
	v_cmp_eq_u32_e32 vcc, v5, v6
	s_cbranch_vccz .Lxb11_spin
	buffer_wbl2 sc1
	s_waitcnt vmcnt(0)
	v_mov_b32_e32 v4, 0x1dc03400
	global_atomic_add v5, v4, v1, s[26:27] sc0
	v_mul_lo_u32 v6, v3, 12
	s_waitcnt vmcnt(0)
	v_add_u32_e32 v5, 1, v5
	v_cmp_eq_u32_e32 vcc, v5, v6
	s_cbranch_vccz .Lxb11_spin
	v_mov_b32_e32 v4, 0x1dc02400
	global_atomic_add v4, v1, s[26:27]
	global_atomic_add v4, v1, s[26:27] offset:256
	global_atomic_add v4, v1, s[26:27] offset:512
	global_atomic_add v4, v1, s[26:27] offset:768
	global_atomic_add v4, v1, s[26:27] offset:1024
	global_atomic_add v4, v1, s[26:27] offset:1280
	global_atomic_add v4, v1, s[26:27] offset:1536
	global_atomic_add v4, v1, s[26:27] offset:1792
	global_atomic_add v4, v1, s[26:27] offset:2048
	global_atomic_add v4, v1, s[26:27] offset:2304
	global_atomic_add v4, v1, s[26:27] offset:2560
	global_atomic_add v4, v1, s[26:27] offset:2816
	global_atomic_add v4, v1, s[26:27] offset:3072
	global_atomic_add v4, v1, s[26:27] offset:3328
	global_atomic_add v4, v1, s[26:27] offset:3584
	global_atomic_add v4, v1, s[26:27] offset:3840
	s_waitcnt vmcnt(0)
	s_branch .Lxb11_done

.Lxb11_loop:
	global_load_dword v5, v4, s[26:27] sc1
	s_waitcnt vmcnt(0)
	v_cmp_ne_u32_e32 vcc, 11, v5
	s_cbranch_vccnz .Lxb11_done
	s_sleep 1
	s_add_u32 s99, s99, 1
	s_cmp_lt_u32 s99, 0x8000
	s_cbranch_scc1 .Lxb11_loop

.LBB0_848:
	s_waitcnt vmcnt(0)
	v_mov_b32_e32 v0, v205
	s_barrier
	s_nop 0
	v_cmp_eq_u32_e32 vcc, 0, v0
	s_and_saveexec_b64 s[4:5], vcc
	s_cbranch_execz .LBB0_900
	v_mov_b32_e32 v0, 0x12000
	ds_read_b64 v[2:3], v0
	s_getreg_b32 s98, hwreg(HW_REG_XCC_ID, 0, 4)
	s_and_b32 s98, s98, 15
	s_lshl_b32 s98, s98, 8
	v_mov_b32_e32 v1, 1
	s_add_u32 s100, s98, 0x1dc01400
	s_add_u32 s101, s98, 0x1dc02400
	v_mov_b32_e32 v4, s100
	s_waitcnt vmcnt(0) expcnt(0) lgkmcnt(0)
	global_atomic_add v5, v4, v1, s[26:27] sc0
	v_mul_lo_u32 v6, v2, 13
	s_waitcnt vmcnt(0)
	v_add_u32_e32 v5, 1, v5
	v_cmp_eq_u32_e32 vcc, v5, v6
	s_cbranch_vccz .Lxb12_spin
	buffer_wbl2 sc1
	s_waitcnt vmcnt(0)
	v_mov_b32_e32 v4, 0x1dc03400
	global_atomic_add v5, v4, v1, s[26:27] sc0
	v_mul_lo_u32 v6, v3, 13
	s_waitcnt vmcnt(0)
	v_add_u32_e32 v5, 1, v5
	v_cmp_eq_u32_e32 vcc, v5, v6
	s_cbranch_vccz .Lxb12_spin
	v_mov_b32_e32 v4, 0x1dc02400
	global_atomic_add v4, v1, s[26:27]
	global_atomic_add v4, v1, s[26:27] offset:256
	global_atomic_add v4, v1, s[26:27] offset:512
	global_atomic_add v4, v1, s[26:27] offset:768
	global_atomic_add v4, v1, s[26:27] offset:1024
	global_atomic_add v4, v1, s[26:27] offset:1280
	global_atomic_add v4, v1, s[26:27] offset:1536
	global_atomic_add v4, v1, s[26:27] offset:1792
	global_atomic_add v4, v1, s[26:27] offset:2048
	global_atomic_add v4, v1, s[26:27] offset:2304
	global_atomic_add v4, v1, s[26:27] offset:2560
	global_atomic_add v4, v1, s[26:27] offset:2816
	global_atomic_add v4, v1, s[26:27] offset:3072
	global_atomic_add v4, v1, s[26:27] offset:3328
	global_atomic_add v4, v1, s[26:27] offset:3584
	global_atomic_add v4, v1, s[26:27] offset:3840
	s_waitcnt vmcnt(0)
	s_branch .Lxb12_done

.Lxb12_loop:
	global_load_dword v5, v4, s[26:27] sc1
	s_waitcnt vmcnt(0)
	v_cmp_ne_u32_e32 vcc, 12, v5
	s_cbranch_vccnz .Lxb12_done
	s_sleep 1
	s_add_u32 s99, s99, 1
	s_cmp_lt_u32 s99, 0x8000
	s_cbranch_scc1 .Lxb12_loop

.LBB0_903:
	s_or_b64 exec, exec, s[6:7]
	s_waitcnt vmcnt(0)
	v_mov_b32_e32 v0, v205
	s_barrier
	s_nop 0
	v_cmp_eq_u32_e32 vcc, 0, v0
	s_and_saveexec_b64 s[4:5], vcc
	s_cbranch_execz .LBB0_955
	v_mov_b32_e32 v0, 0x12000
	ds_read_b64 v[2:3], v0
	s_getreg_b32 s98, hwreg(HW_REG_XCC_ID, 0, 4)
	s_and_b32 s98, s98, 15
	s_lshl_b32 s98, s98, 8
	v_mov_b32_e32 v1, 1
	s_add_u32 s100, s98, 0x1dc01400
	s_add_u32 s101, s98, 0x1dc02400
	v_mov_b32_e32 v4, s100
	s_waitcnt vmcnt(0) expcnt(0) lgkmcnt(0)
	global_atomic_add v5, v4, v1, s[26:27] sc0
	v_mul_lo_u32 v6, v2, 14
	s_waitcnt vmcnt(0)
	v_add_u32_e32 v5, 1, v5
	v_cmp_eq_u32_e32 vcc, v5, v6
	s_cbranch_vccz .Lxb13_spin
	buffer_wbl2 sc1
	s_waitcnt vmcnt(0)
	v_mov_b32_e32 v4, 0x1dc03400
	global_atomic_add v5, v4, v1, s[26:27] sc0
	v_mul_lo_u32 v6, v3, 14
	s_waitcnt vmcnt(0)
	v_add_u32_e32 v5, 1, v5
	v_cmp_eq_u32_e32 vcc, v5, v6
	s_cbranch_vccz .Lxb13_spin
	v_mov_b32_e32 v4, 0x1dc02400
	global_atomic_add v4, v1, s[26:27]
	global_atomic_add v4, v1, s[26:27] offset:256
	global_atomic_add v4, v1, s[26:27] offset:512
	global_atomic_add v4, v1, s[26:27] offset:768
	global_atomic_add v4, v1, s[26:27] offset:1024
	global_atomic_add v4, v1, s[26:27] offset:1280
	global_atomic_add v4, v1, s[26:27] offset:1536
	global_atomic_add v4, v1, s[26:27] offset:1792
	global_atomic_add v4, v1, s[26:27] offset:2048
	global_atomic_add v4, v1, s[26:27] offset:2304
	global_atomic_add v4, v1, s[26:27] offset:2560
	global_atomic_add v4, v1, s[26:27] offset:2816
	global_atomic_add v4, v1, s[26:27] offset:3072
	global_atomic_add v4, v1, s[26:27] offset:3328
	global_atomic_add v4, v1, s[26:27] offset:3584
	global_atomic_add v4, v1, s[26:27] offset:3840
	s_waitcnt vmcnt(0)
	s_branch .Lxb13_done

.Lxb13_loop:
	global_load_dword v5, v4, s[26:27] sc1
	s_waitcnt vmcnt(0)
	v_cmp_ne_u32_e32 vcc, 13, v5
	s_cbranch_vccnz .Lxb13_done
	s_sleep 1
	s_add_u32 s99, s99, 1
	s_cmp_lt_u32 s99, 0x8000
	s_cbranch_scc1 .Lxb13_loop

.LBB0_970:
	s_waitcnt vmcnt(0)
	v_mov_b32_e32 v0, v205
	s_barrier
	s_nop 0
	v_cmp_eq_u32_e32 vcc, 0, v0
	s_and_saveexec_b64 s[0:1], vcc
	s_cbranch_execz .LBB0_1022
	v_mov_b32_e32 v0, 0x12000
	ds_read_b64 v[2:3], v0
	s_getreg_b32 s98, hwreg(HW_REG_XCC_ID, 0, 4)
	s_and_b32 s98, s98, 15
	s_lshl_b32 s98, s98, 8
	v_mov_b32_e32 v1, 1
	s_add_u32 s100, s98, 0x1dc01400
	s_add_u32 s101, s98, 0x1dc02400
	v_mov_b32_e32 v4, s100
	s_waitcnt vmcnt(0) expcnt(0) lgkmcnt(0)
	global_atomic_add v5, v4, v1, s[26:27] sc0
	v_mul_lo_u32 v6, v2, 15
	s_waitcnt vmcnt(0)
	v_add_u32_e32 v5, 1, v5
	v_cmp_eq_u32_e32 vcc, v5, v6
	s_cbranch_vccz .Lxb14_spin
	buffer_wbl2 sc1
	s_waitcnt vmcnt(0)
	v_mov_b32_e32 v4, 0x1dc03400
	global_atomic_add v5, v4, v1, s[26:27] sc0
	v_mul_lo_u32 v6, v3, 15
	s_waitcnt vmcnt(0)
	v_add_u32_e32 v5, 1, v5
	v_cmp_eq_u32_e32 vcc, v5, v6
	s_cbranch_vccz .Lxb14_spin
	v_mov_b32_e32 v4, 0x1dc02400
	global_atomic_add v4, v1, s[26:27]
	global_atomic_add v4, v1, s[26:27] offset:256
	global_atomic_add v4, v1, s[26:27] offset:512
	global_atomic_add v4, v1, s[26:27] offset:768
	global_atomic_add v4, v1, s[26:27] offset:1024
	global_atomic_add v4, v1, s[26:27] offset:1280
	global_atomic_add v4, v1, s[26:27] offset:1536
	global_atomic_add v4, v1, s[26:27] offset:1792
	global_atomic_add v4, v1, s[26:27] offset:2048
	global_atomic_add v4, v1, s[26:27] offset:2304
	global_atomic_add v4, v1, s[26:27] offset:2560
	global_atomic_add v4, v1, s[26:27] offset:2816
	global_atomic_add v4, v1, s[26:27] offset:3072
	global_atomic_add v4, v1, s[26:27] offset:3328
	global_atomic_add v4, v1, s[26:27] offset:3584
	global_atomic_add v4, v1, s[26:27] offset:3840
	s_waitcnt vmcnt(0)
	s_branch .Lxb14_done

.Lxb14_loop:
	global_load_dword v5, v4, s[26:27] sc1
	s_waitcnt vmcnt(0)
	v_cmp_ne_u32_e32 vcc, 14, v5
	s_cbranch_vccnz .Lxb14_done
	s_sleep 1
	s_add_u32 s99, s99, 1
	s_cmp_lt_u32 s99, 0x8000
	s_cbranch_scc1 .Lxb14_loop

.LBB0_1045:
	s_or_b64 exec, exec, s[2:3]
	s_waitcnt vmcnt(0)
	v_mov_b32_e32 v0, v205
	s_barrier
	s_nop 0
	v_cmp_eq_u32_e32 vcc, 0, v0
	s_and_saveexec_b64 s[0:1], vcc
	s_cbranch_execz .LBB0_1097
	v_mov_b32_e32 v0, 0x12000
	ds_read_b64 v[2:3], v0
	s_getreg_b32 s98, hwreg(HW_REG_XCC_ID, 0, 4)
	s_and_b32 s98, s98, 15
	s_lshl_b32 s98, s98, 8
	v_mov_b32_e32 v1, 1
	s_add_u32 s100, s98, 0x1dc01400
	s_add_u32 s101, s98, 0x1dc02400
	v_mov_b32_e32 v4, s100
	s_waitcnt vmcnt(0) expcnt(0) lgkmcnt(0)
	global_atomic_add v5, v4, v1, s[26:27] sc0
	v_mul_lo_u32 v6, v2, 16
	s_waitcnt vmcnt(0)
	v_add_u32_e32 v5, 1, v5
	v_cmp_eq_u32_e32 vcc, v5, v6
	s_cbranch_vccz .Lxb15_spin
	buffer_wbl2 sc1
	s_waitcnt vmcnt(0)
	v_mov_b32_e32 v4, 0x1dc03400
	global_atomic_add v5, v4, v1, s[26:27] sc0
	v_mul_lo_u32 v6, v3, 16
	s_waitcnt vmcnt(0)
	v_add_u32_e32 v5, 1, v5
	v_cmp_eq_u32_e32 vcc, v5, v6
	s_cbranch_vccz .Lxb15_spin
	v_mov_b32_e32 v4, 0x1dc02400
	global_atomic_add v4, v1, s[26:27]
	global_atomic_add v4, v1, s[26:27] offset:256
	global_atomic_add v4, v1, s[26:27] offset:512
	global_atomic_add v4, v1, s[26:27] offset:768
	global_atomic_add v4, v1, s[26:27] offset:1024
	global_atomic_add v4, v1, s[26:27] offset:1280
	global_atomic_add v4, v1, s[26:27] offset:1536
	global_atomic_add v4, v1, s[26:27] offset:1792
	global_atomic_add v4, v1, s[26:27] offset:2048
	global_atomic_add v4, v1, s[26:27] offset:2304
	global_atomic_add v4, v1, s[26:27] offset:2560
	global_atomic_add v4, v1, s[26:27] offset:2816
	global_atomic_add v4, v1, s[26:27] offset:3072
	global_atomic_add v4, v1, s[26:27] offset:3328
	global_atomic_add v4, v1, s[26:27] offset:3584
	global_atomic_add v4, v1, s[26:27] offset:3840
	s_waitcnt vmcnt(0)
	s_branch .Lxb15_done

.Lxb15_loop:
	global_load_dword v5, v4, s[26:27] sc1
	s_waitcnt vmcnt(0)
	v_cmp_ne_u32_e32 vcc, 15, v5
	s_cbranch_vccnz .Lxb15_done
	s_sleep 1
	s_add_u32 s99, s99, 1
	s_cmp_lt_u32 s99, 0x8000
	s_cbranch_scc1 .Lxb15_loop
